# phase 0: weight transpose tiles in a hand-written double-buffered loop with scalar tile decode; generic item loop keeps adaLN + rope items
# speedup vs baseline: 1.0512x; 1.0031x over previous
; __device__ __forceinline__ void phase0(const Params& p, unsigned char* smem) {
;     int tid = threadIdx.x; asm volatile("" : "+v"(tid));
;     constexpr int N_ADA = 192, N_WT = 4352;
;     for (int item = blockIdx.x; item < N_ADA + N_WT + 1; item += gridDim.x) {
;         if (item < N_ADA) {
;             float* ssc = (float*)smem;
;             float* red = ssc + 9 * 1024;
;             const int l = item / 48, n0 = (item % 48) * 64;
;             __syncthreads();
;             for (int idx = tid; idx < 9 * 1024; idx += NTHR) {
;                 const int v = idx >> 10, kk = idx & 1023;
;                 const float cv = v < 8 ? p.c[v * 1024 + kk] : p.c_ctx[kk];
;                 ssc[idx] = cv / (1.0f + expf(-cv));
;             }
;             __syncthreads();
;             const int kg = tid >> 6, col = tid & 63;
;             float acc[9];
; #pragma unroll
;             for (int v = 0; v < 9; ++v) acc[v] = 0.f;
;             const float* wp = p.ada_w + ((size_t)l * 1024 + kg * 128) * 3072 + n0 + col;
;     ...
;             for (int idx = tid; idx < 1024; idx += NTHR) {
;                 const int pos = idx >> 4, f = idx & 15;
;                 const float angf = (float)pos * INVF[f];
;                 const double a = (double)angf;
;                 const double kq = rint(a * 0.63661977236758134308);
;                 const double r = a - kq * 1.57079632679489661923;
;                 const double r2 = r * r;
;                 double sn = r * (1.0 + r2 * (-1.0 / 6 + r2 * (1.0 / 120 + r2 * (-1.0 / 5040 + r2 * (1.0 / 362880 + r2 * (-1.0 / 39916800 + r2 * (1.0 / 6227020800.0)))))));
;                 double cs = 1.0 + r2 * (-0.5 + r2 * (1.0 / 24 + r2 * (-1.0 / 720 + r2 * (1.0 / 40320 + r2 * (-1.0 / 3628800 + r2 * (1.0 / 479001600.0))))));
.LBB0_2:
	s_or_b64 exec, exec, s[4:5]
	s_load_dword s33, s[0:1], 0x190
	s_load_dwordx16 s[8:23], s[0:1], 0x0
	s_load_dwordx16 s[36:51], s[0:1], 0x40
	v_mov_b32_e32 v70, v234
	s_cmpk_gt_i32 s94, 0x11c0
	s_waitcnt lgkmcnt(0)
	v_writelane_b32 v253, s36, 16
	s_nop 1
	v_writelane_b32 v253, s37, 17
	v_writelane_b32 v253, s38, 18
	v_writelane_b32 v253, s39, 19
	v_writelane_b32 v253, s40, 20
	v_writelane_b32 v253, s41, 21
	v_writelane_b32 v253, s42, 22
	v_writelane_b32 v253, s43, 23
	v_writelane_b32 v253, s44, 24
	v_writelane_b32 v253, s45, 25
	v_writelane_b32 v253, s46, 26
	v_writelane_b32 v253, s47, 27
	v_writelane_b32 v253, s48, 28
	v_writelane_b32 v253, s49, 29
	v_writelane_b32 v253, s50, 30
	v_writelane_b32 v253, s51, 31
	s_load_dwordx16 s[36:51], s[0:1], 0xc0
	s_waitcnt lgkmcnt(0)
	v_writelane_b32 v253, s36, 32
	s_nop 1
	v_writelane_b32 v253, s37, 33
	v_writelane_b32 v253, s38, 34
	v_writelane_b32 v253, s39, 35
	v_writelane_b32 v253, s40, 36
	v_writelane_b32 v253, s41, 37
	v_writelane_b32 v253, s42, 38
	v_writelane_b32 v253, s43, 39
	v_writelane_b32 v253, s44, 40
	v_writelane_b32 v253, s45, 41
	v_writelane_b32 v253, s46, 42
	v_writelane_b32 v253, s47, 43
	v_writelane_b32 v253, s48, 44
	v_writelane_b32 v253, s49, 45
	v_writelane_b32 v253, s50, 46
	v_writelane_b32 v253, s51, 47
	v_writelane_b32 v253, s8, 48
	s_nop 1
	v_writelane_b32 v253, s9, 49
	v_writelane_b32 v253, s10, 50
	v_writelane_b32 v253, s11, 51
	v_writelane_b32 v253, s12, 52
	v_writelane_b32 v253, s13, 53
	v_writelane_b32 v253, s14, 54
	v_writelane_b32 v253, s15, 55
	v_writelane_b32 v253, s16, 56
	v_writelane_b32 v253, s17, 57
	v_writelane_b32 v253, s18, 58
	v_writelane_b32 v253, s19, 59
	v_writelane_b32 v253, s20, 60
	v_writelane_b32 v253, s21, 61
	v_writelane_b32 v253, s22, 62
	v_writelane_b32 v253, s23, 63
	s_cbranch_scc1 .LBB0_83
	v_lshlrev_b32_e32 v4, 3, v70
	s_movk_i32 s4, 0x104
	s_mov_b64 s[26:27], s[22:23]
	v_ashrrev_i32_e32 v115, 3, v70
	v_and_b32_e32 v4, 56, v4
	v_lshlrev_b32_e32 v114, 2, v70
	s_mov_b64 s[24:25], s[20:21]
	s_mov_b64 s[22:23], s[18:19]
	s_mov_b64 s[20:21], s[16:17]
	s_mov_b64 s[18:19], s[14:15]
	s_mov_b64 s[16:17], s[12:13]
	s_mov_b64 s[14:15], s[10:11]
	s_mov_b64 s[12:13], s[8:9]
	v_mul_lo_u32 v5, v115, s4
	v_lshlrev_b32_e32 v6, 2, v4
	v_and_b32_e32 v7, 15, v70
	v_ashrrev_i32_e32 v1, 4, v70
	v_and_b32_e32 v2, 60, v114
	v_mov_b32_e32 v73, 0
	v_add3_u32 v116, 0, v5, v6
	v_lshlrev_b32_e32 v5, 2, v115
	v_and_b32_e32 v6, 31, v115
	s_movk_i32 s4, 0x80
	v_lshlrev_b32_e32 v72, 2, v7
	s_getpc_b64 s[12:13]
	s_add_u32 s12, s12, INVF@rel32@lo+4
	s_addc_u32 s13, s13, INVF@rel32@hi+12
	s_load_dwordx16 s[36:51], s[0:1], 0x140
	v_mul_u32_u24_e32 v3, 0x104, v2
	v_and_or_b32 v117, v5, s4, v6
	v_ashrrev_i32_e32 v5, 6, v70
	v_lshlrev_b32_e32 v9, 2, v1
	v_lshl_add_u64 v[74:75], s[12:13], 0, v[72:73]
	s_movk_i32 s12, 0x900
	v_lshlrev_b32_e32 v8, 7, v5
	v_lshl_add_u32 v119, v5, 9, 0
	v_add3_u32 v121, 0, v3, v9
	v_mul_lo_u32 v3, v5, s12
	v_max_i32_e32 v5, 0x2200, v70
	v_and_b32_e32 v118, 63, v70
	v_sub_u32_e32 v5, v5, v70
	v_lshlrev_b32_e32 v6, 2, v118
	v_mov_b32_e32 v7, v73
	v_add_u32_e32 v5, 0x1ff, v5
	s_waitcnt lgkmcnt(0)
	v_lshl_add_u64 v[76:77], s[46:47], 0, v[6:7]
	v_lshrrev_b32_e32 v7, 9, v5
	s_movk_i32 s50, 0x1ff
	v_add_u32_e32 v9, 1, v7
	v_cmp_lt_u32_e64 s[12:13], s50, v5
	v_and_b32_e32 v5, 0xfffffe, v9
	s_movk_i32 s51, 0x3000
	v_add_u32_e32 v7, -1, v7
	v_cmp_ne_u32_e64 s[18:19], v9, v5
	v_mad_i64_i32 v[8:9], s[20:21], v8, s51, 0
	v_lshrrev_b32_e32 v10, 1, v7
	v_cmp_lt_u32_e64 s[14:15], 1, v7
	v_and_b32_e32 v7, 2, v7
	v_or_b32_e32 v8, v8, v6
	s_movk_i32 s4, 0x400
	s_movk_i32 s8, 0x2400
	v_add_u32_e32 v120, 0, v6
	s_movk_i32 s10, 0x240
	v_add_u32_e32 v10, 1, v10
	v_cmp_eq_u32_e64 s[16:17], 0, v7
	v_lshl_add_u64 v[6:7], s[22:23], 0, v[8:9]
	s_mov_b64 s[20:21], 0x15000
	s_mov_b32 s34, 0x6dc9c883
	s_mov_b32 s36, 0x54442d18
	s_mov_b32 s38, 0x13a86d09
	s_mov_b32 s40, 0xeff8d898
	s_mov_b32 s27, 0
	v_cmp_gt_i32_e64 s[4:5], s4, v70
	v_cmp_eq_u32_e64 s[6:7], 0, v70
	v_cmp_gt_i32_e64 s[8:9], s8, v70
	v_cmp_gt_i32_e64 s[10:11], s10, v70
	v_lshl_add_u32 v122, v5, 9, v70
	v_add_u32_e32 v71, 0x200, v70
	v_and_b32_e32 v123, -2, v10
	v_lshlrev_b32_e32 v124, 1, v70
	v_add_u32_e32 v125, 0, v114
	v_lshl_add_u64 v[78:79], v[6:7], 0, s[20:21]
	v_lshlrev_b32_e32 v80, 2, v2
	v_lshlrev_b32_e32 v82, 1, v4
	s_mov_b32 s35, 0x3fe45f30
	s_mov_b32 s37, 0xbff921fb
	s_mov_b32 s39, 0x3de61246
	s_mov_b32 s41, 0x3e21eed8
	s_mov_b32 s52, 0x3fb8aa3b
	s_mov_b32 s53, 0xc2ce8ed0
	s_mov_b32 s54, 0x42b17218
	s_movk_i32 s55, 0x2000
	s_mov_b32 s56, 0xbfb8aa3b
	s_mov_b32 s57, 0x42ce8ed0
	s_mov_b32 s58, 0xc2b17218
	v_add_u32_e32 v126, v120, v3
	v_mov_b32_e32 v84, 0x67f544e4
	v_mov_b32_e32 v85, 0xbe5ae645
	v_mov_b32_e32 v86, 0xa556c734
	v_mov_b32_e32 v87, 0x3ec71de3
	v_mov_b32_e32 v88, 0x1a01a01a
	v_mov_b32_e32 v89, 0xbf2a01a0
	v_mov_b32_e32 v90, 0x11111111
	v_mov_b32_e32 v91, 0x3f811111
	v_mov_b32_e32 v92, 0x55555555
	v_mov_b32_e32 v93, 0xbfc55555
	v_mov_b32_e32 v94, 0xb7789f5c
	v_mov_b32_e32 v95, 0xbe927e4f
	v_mov_b32_e32 v97, 0x3efa01a0
	v_mov_b32_e32 v98, 0x16c16c17
	v_mov_b32_e32 v99, 0xbf56c16c
	v_mov_b32_e32 v101, 0x3fa55555
	v_mov_b32_e32 v127, 0x7f800000
	s_mov_b32 s59, s94
	s_cmpk_lt_u32 s94, 0xc0
	s_cbranch_scc1 .LBB0_6
	s_movk_i32 s59, 0x11c0
	s_cmpk_eq_u32 s94, 0xc0
	s_cbranch_scc1 .LBB0_6
	s_branch .LBB0_82

; __device__ __forceinline__ void phase0(const Params& p, unsigned char* smem) {
;     ...
;     for (int item = blockIdx.x; item < N_ADA + N_WT + 1; item += gridDim.x) {
;         if (item < N_ADA) {
.LBB0_5:
	s_movk_i32 s59, 0x11c1
	s_cmpk_lt_i32 s59, 0x11c1
	s_cbranch_scc0 .LBB0_82

; __host__ __device__ __forceinline__ int layer_N(int l) { return (l == 0 || l == 3) ? 2560 : 4096; }
; __device__ __forceinline__ void phase0(const Params& p, unsigned char* smem) {
;     ...
;             int t = item - N_ADA;
;             const float* W; bf16_t* Wt; int N; int nperm = 0;
;             int l = 0; bool found = false;
; #pragma unroll
;             for (int m = 0; m < 4; ++m) {
;                 const int ntl = 16 * (layer_N(m) / 64);
;                 if (!found) { if (t < ntl) { l = m; found = true; } else t -= ntl; }
;             }
;             if (found) { W = sel4(p.w_in, l); Wt = sel4(p.wt_in, l); N = layer_N(l); nperm = 1024 + ((l == 0 || l == 3) ? 256 : 1024); }
;             else { l = t / 256; t = t % 256; W = sel4(p.w_out, l); Wt = sel4(p.wt_out, l); N = 1024; }
;             const int k0 = (t & 15) * 64, n0 = (t >> 4) * 64;
;             float* sT = (float*)smem;
;             float4 v[2];
; #pragma unroll
;             for (int i = 0; i < 2; ++i) {
;                 const int kk = (tid >> 4) + 32 * i, n4 = (tid & 15) * 4;
;                 v[i] = *(const float4*)(W + (size_t)(k0 + kk) * N + n0 + n4);
;             }
;     ...
;                 int f = n0 + n;
;                 if (f < nperm) { const int fl = f & 255, hh = fl >> 6, d = fl & 63; f = (f & ~255) + 128 * (d >> 5) + 32 * hh + (d & 31); }
;                 *(u32x4*)(Wt + (size_t)f * 1024 + k0 + k8) = o;
.LBB0_82:
	s_barrier
	s_mov_b32 s4, s94
	v_lshrrev_b32_e32 v5, 4, v234
	v_and_b32_e32 v1, 15, v234
	v_lshlrev_b32_e32 v6, 4, v1
	v_mul_u32_u24_e32 v7, 0x104, v1
	v_add_lshl_u32 v7, v7, v5, 2
	v_lshrrev_b32_e32 v1, 3, v234
	v_and_b32_e32 v2, 7, v234
	v_mul_u32_u24_e32 v8, 0x41, v1
	v_lshl_add_u32 v8, v2, 3, v8
	v_lshlrev_b32_e32 v8, 2, v8
	v_lshlrev_b32_e32 v2, 4, v2
	v_lshl_add_u32 v10, v1, 11, v2
	v_lshrrev_b32_e32 v9, 5, v1
	v_lshlrev_b32_e32 v9, 7, v9
	v_and_b32_e32 v1, 31, v1
	v_add_u32_e32 v9, v9, v1
	v_lshl_add_u32 v9, v9, 11, v2
	s_cmpk_lt_u32 s4, 0xd00
	s_cbranch_scc0 .Lwt_out_1
	s_movk_i32 s12, 3
	s_movk_i32 s13, 0xa80
	s_cmpk_lt_u32 s4, 0xa80
	s_cselect_b32 s12, 2, s12
	s_cselect_b32 s13, 0x680, s13
	s_cmpk_lt_u32 s4, 0x680
	s_cselect_b32 s12, 1, s12
	s_cselect_b32 s13, 0x280, s13
	s_cmpk_lt_u32 s4, 0x280
	s_cselect_b32 s12, 0, s12
	s_cselect_b32 s13, 0, s13
	s_sub_i32 s13, s4, s13
	s_add_i32 s5, s12, 1
	s_and_b32 s5, s5, 2
	s_movk_i32 s27, 0x2800
	s_cmp_eq_u32 s5, 0
	s_cselect_b32 s10, s27, 0x4000
	s_movk_i32 s27, 0x500
	s_cselect_b32 s11, s27, 0x800
	s_lshl_b32 s5, s12, 1
	s_add_i32 s5, s5, 14
	s_cmp_eq_u32 s12, 0
	s_cselect_b32 s5, 62, s5
	v_readlane_b32 s6, v253, s5
	s_add_i32 s5, s5, 1
	v_readlane_b32 s7, v253, s5
	s_mov_b64 s[8:9], s[70:71]
	s_cmp_eq_u32 s12, 1
	s_cselect_b64 s[8:9], s[72:73], s[8:9]
	s_cmp_eq_u32 s12, 2
	s_cselect_b64 s[8:9], s[74:75], s[8:9]
	s_cmp_eq_u32 s12, 3
	s_cbranch_scc0 .Lwt_com_1
	v_readlane_b32 s8, v253, 0
	v_readlane_b32 s9, v253, 1
	s_branch .Lwt_com_1
.Lwt_out_1:
	s_sub_i32 s13, s4, 0xd00
	s_lshr_b32 s12, s13, 8
	s_and_b32 s13, s13, 0xff
	s_movk_i32 s10, 0x1000
	s_mov_b32 s11, 0
	s_lshl_b32 s5, s12, 1
	s_add_i32 s27, s5, 22
	v_readlane_b32 s6, v253, s27
	s_add_i32 s27, s27, 1
	v_readlane_b32 s7, v253, s27
	s_add_i32 s27, s5, 2
	v_readlane_b32 s8, v253, s27
	s_add_i32 s27, s27, 1
	v_readlane_b32 s9, v253, s27
.Lwt_com_1:
	s_and_b32 s14, s13, 15
	s_lshl_b32 s14, s14, 6
	s_lshr_b32 s15, s13, 4
	s_lshl_b32 s15, s15, 6
	s_mul_i32 s5, s14, s10
	s_lshl_b32 s27, s15, 2
	s_add_u32 s5, s5, s27
	s_add_u32 s16, s6, s5
	s_addc_u32 s17, s7, 0
	s_lshl_b32 s5, s10, 5
	s_add_u32 s18, s16, s5
	s_addc_u32 s19, s17, 0
	v_mul_lo_u32 v11, v5, s10
	v_add_u32_e32 v11, v11, v6
	global_load_dwordx4 v[16:19], v11, s[16:17]
	global_load_dwordx4 v[20:23], v11, s[18:19]
	s_and_b32 s5, s15, 0xffffff00
	s_lshr_b32 s27, s15, 6
	s_and_b32 s27, s27, 3
	s_lshl_b32 s27, s27, 5
	s_add_i32 s5, s5, s27
	s_cmp_lt_u32 s15, s11
	s_cselect_b32 s5, s5, s15
	s_cselect_b64 s[22:23], -1, 0
	v_cndmask_b32_e64 v12, v10, v9, s[22:23]
	s_lshl_b32 s5, s5, 11
	s_lshl_b32 s27, s14, 1
	s_add_u32 s5, s5, s27
	s_add_u32 s20, s8, s5
	s_addc_u32 s21, s9, 0
	s_add_i32 s4, s4, s92
	s_cmpk_lt_u32 s4, 0xd00
	s_cbranch_scc0 .Lwt_out_2
	s_movk_i32 s12, 3
	s_movk_i32 s13, 0xa80
	s_cmpk_lt_u32 s4, 0xa80
	s_cselect_b32 s12, 2, s12
	s_cselect_b32 s13, 0x680, s13
	s_cmpk_lt_u32 s4, 0x680
	s_cselect_b32 s12, 1, s12
	s_cselect_b32 s13, 0x280, s13
	s_cmpk_lt_u32 s4, 0x280
	s_cselect_b32 s12, 0, s12
	s_cselect_b32 s13, 0, s13
	s_sub_i32 s13, s4, s13
	s_add_i32 s5, s12, 1
	s_and_b32 s5, s5, 2
	s_movk_i32 s27, 0x2800
	s_cmp_eq_u32 s5, 0
	s_cselect_b32 s10, s27, 0x4000
	s_movk_i32 s27, 0x500
	s_cselect_b32 s11, s27, 0x800
	s_lshl_b32 s5, s12, 1
	s_add_i32 s5, s5, 14
	s_cmp_eq_u32 s12, 0
	s_cselect_b32 s5, 62, s5
	v_readlane_b32 s6, v253, s5
	s_add_i32 s5, s5, 1
	v_readlane_b32 s7, v253, s5
	s_mov_b64 s[8:9], s[70:71]
	s_cmp_eq_u32 s12, 1
	s_cselect_b64 s[8:9], s[72:73], s[8:9]
	s_cmp_eq_u32 s12, 2
	s_cselect_b64 s[8:9], s[74:75], s[8:9]
	s_cmp_eq_u32 s12, 3
	s_cbranch_scc0 .Lwt_com_2
	v_readlane_b32 s8, v253, 0
	v_readlane_b32 s9, v253, 1
	s_branch .Lwt_com_2

; __device__ __forceinline__ void phase0(const Params& p, unsigned char* smem) {
;     ...
;             __syncthreads();
; #pragma unroll
;             for (int i = 0; i < 2; ++i) {
;                 const int kk = (tid >> 4) + 32 * i, n4 = (tid & 15) * 4;
;                 sT[(n4 + 0) * 65 + kk] = v[i].x; sT[(n4 + 1) * 65 + kk] = v[i].y;
;                 sT[(n4 + 2) * 65 + kk] = v[i].z; sT[(n4 + 3) * 65 + kk] = v[i].w;
;             }
;             __syncthreads();
;             {
;                 const int n = tid >> 3, k8 = (tid & 7) * 8;
;                 const float* s = sT + n * 65 + k8;
;                 u32x4 o; o.x = pk_bf16(s[0], s[1]); o.y = pk_bf16(s[2], s[3]); o.z = pk_bf16(s[4], s[5]); o.w = pk_bf16(s[6], s[7]);
;                 int f = n0 + n;
;                 if (f < nperm) { const int fl = f & 255, hh = fl >> 6, d = fl & 63; f = (f & ~255) + 128 * (d >> 5) + 32 * hh + (d & 31); }
;                 *(u32x4*)(Wt + (size_t)f * 1024 + k0 + k8) = o;
.Lwt_com_2:
	s_and_b32 s14, s13, 15
	s_lshl_b32 s14, s14, 6
	s_lshr_b32 s15, s13, 4
	s_lshl_b32 s15, s15, 6
	s_mul_i32 s5, s14, s10
	s_lshl_b32 s27, s15, 2
	s_add_u32 s5, s5, s27
	s_add_u32 s16, s6, s5
	s_addc_u32 s17, s7, 0
	s_lshl_b32 s5, s10, 5
	s_add_u32 s18, s16, s5
	s_addc_u32 s19, s17, 0
	v_mul_lo_u32 v11, v5, s10
	v_add_u32_e32 v11, v11, v6
	global_load_dwordx4 v[24:27], v11, s[16:17]
	global_load_dwordx4 v[28:31], v11, s[18:19]
	s_and_b32 s5, s15, 0xffffff00
	s_lshr_b32 s27, s15, 6
	s_and_b32 s27, s27, 3
	s_lshl_b32 s27, s27, 5
	s_add_i32 s5, s5, s27
	s_cmp_lt_u32 s15, s11
	s_cselect_b32 s5, s5, s15
	s_cselect_b64 s[34:35], -1, 0
	v_cndmask_b32_e64 v13, v10, v9, s[34:35]
	s_lshl_b32 s5, s5, 11
	s_lshl_b32 s27, s14, 1
	s_add_u32 s5, s5, s27
	s_add_u32 s24, s8, s5
	s_addc_u32 s25, s9, 0
	s_add_i32 s4, s4, s92
	s_waitcnt vmcnt(2)
	s_barrier
	ds_write2_b32 v7, v16, v20 offset1:32
	ds_write2_b32 v7, v17, v21 offset0:65 offset1:97
	ds_write2_b32 v7, v18, v22 offset0:130 offset1:162
	ds_write2_b32 v7, v19, v23 offset0:195 offset1:227
	s_waitcnt lgkmcnt(0)
	s_barrier
	ds_read2_b32 v[32:33], v8 offset1:1
	ds_read2_b32 v[34:35], v8 offset0:2 offset1:3
	ds_read2_b32 v[36:37], v8 offset0:4 offset1:5
	ds_read2_b32 v[38:39], v8 offset0:6 offset1:7
	s_waitcnt lgkmcnt(0)
	v_cvt_pk_bf16_f32 v40, v32, v33
	v_cvt_pk_bf16_f32 v41, v34, v35
	v_cvt_pk_bf16_f32 v42, v36, v37
	v_cvt_pk_bf16_f32 v43, v38, v39
	global_store_dwordx4 v12, v[40:43], s[20:21]
	s_movk_i32 s26, 7
.Lwt_loop:
	s_cmpk_lt_u32 s4, 0xd00
	s_cbranch_scc0 .Lwt_out_3
	s_movk_i32 s12, 3
	s_movk_i32 s13, 0xa80
	s_cmpk_lt_u32 s4, 0xa80
	s_cselect_b32 s12, 2, s12
	s_cselect_b32 s13, 0x680, s13
	s_cmpk_lt_u32 s4, 0x680
	s_cselect_b32 s12, 1, s12
	s_cselect_b32 s13, 0x280, s13
	s_cmpk_lt_u32 s4, 0x280
	s_cselect_b32 s12, 0, s12
	s_cselect_b32 s13, 0, s13
	s_sub_i32 s13, s4, s13
	s_add_i32 s5, s12, 1
	s_and_b32 s5, s5, 2
	s_movk_i32 s27, 0x2800
	s_cmp_eq_u32 s5, 0
	s_cselect_b32 s10, s27, 0x4000
	s_movk_i32 s27, 0x500
	s_cselect_b32 s11, s27, 0x800
	s_lshl_b32 s5, s12, 1
	s_add_i32 s5, s5, 14
	s_cmp_eq_u32 s12, 0
	s_cselect_b32 s5, 62, s5
	v_readlane_b32 s6, v253, s5
	s_add_i32 s5, s5, 1
	v_readlane_b32 s7, v253, s5
	s_mov_b64 s[8:9], s[70:71]
	s_cmp_eq_u32 s12, 1
	s_cselect_b64 s[8:9], s[72:73], s[8:9]
	s_cmp_eq_u32 s12, 2
	s_cselect_b64 s[8:9], s[74:75], s[8:9]
	s_cmp_eq_u32 s12, 3
	s_cbranch_scc0 .Lwt_com_3
	v_readlane_b32 s8, v253, 0
	v_readlane_b32 s9, v253, 1
	s_branch .Lwt_com_3

; __device__ __forceinline__ void phase0(const Params& p, unsigned char* smem) {
;     ...
;             float4 v[2];
; #pragma unroll
;             for (int i = 0; i < 2; ++i) {
;                 const int kk = (tid >> 4) + 32 * i, n4 = (tid & 15) * 4;
;                 v[i] = *(const float4*)(W + (size_t)(k0 + kk) * N + n0 + n4);
;             }
;             __syncthreads();
; #pragma unroll
;             for (int i = 0; i < 2; ++i) {
;                 const int kk = (tid >> 4) + 32 * i, n4 = (tid & 15) * 4;
;                 sT[(n4 + 0) * 65 + kk] = v[i].x; sT[(n4 + 1) * 65 + kk] = v[i].y;
;                 sT[(n4 + 2) * 65 + kk] = v[i].z; sT[(n4 + 3) * 65 + kk] = v[i].w;
;             }
;             __syncthreads();
;             {
;                 const int n = tid >> 3, k8 = (tid & 7) * 8;
;                 const float* s = sT + n * 65 + k8;
;                 u32x4 o; o.x = pk_bf16(s[0], s[1]); o.y = pk_bf16(s[2], s[3]); o.z = pk_bf16(s[4], s[5]); o.w = pk_bf16(s[6], s[7]);
;                 int f = n0 + n;
;                 if (f < nperm) { const int fl = f & 255, hh = fl >> 6, d = fl & 63; f = (f & ~255) + 128 * (d >> 5) + 32 * hh + (d & 31); }
;                 *(u32x4*)(Wt + (size_t)f * 1024 + k0 + k8) = o;
.Lwt_com_3:
	s_and_b32 s14, s13, 15
	s_lshl_b32 s14, s14, 6
	s_lshr_b32 s15, s13, 4
	s_lshl_b32 s15, s15, 6
	s_mul_i32 s5, s14, s10
	s_lshl_b32 s27, s15, 2
	s_add_u32 s5, s5, s27
	s_add_u32 s16, s6, s5
	s_addc_u32 s17, s7, 0
	s_lshl_b32 s5, s10, 5
	s_add_u32 s18, s16, s5
	s_addc_u32 s19, s17, 0
	v_mul_lo_u32 v11, v5, s10
	v_add_u32_e32 v11, v11, v6
	global_load_dwordx4 v[16:19], v11, s[16:17]
	global_load_dwordx4 v[20:23], v11, s[18:19]
	s_and_b32 s5, s15, 0xffffff00
	s_lshr_b32 s27, s15, 6
	s_and_b32 s27, s27, 3
	s_lshl_b32 s27, s27, 5
	s_add_i32 s5, s5, s27
	s_cmp_lt_u32 s15, s11
	s_cselect_b32 s5, s5, s15
	s_cselect_b64 s[22:23], -1, 0
	v_cndmask_b32_e64 v12, v10, v9, s[22:23]
	s_lshl_b32 s5, s5, 11
	s_lshl_b32 s27, s14, 1
	s_add_u32 s5, s5, s27
	s_add_u32 s20, s8, s5
	s_addc_u32 s21, s9, 0
	s_add_i32 s4, s4, s92
	s_waitcnt vmcnt(3)
	s_barrier
	ds_write2_b32 v7, v24, v28 offset1:32
	ds_write2_b32 v7, v25, v29 offset0:65 offset1:97
	ds_write2_b32 v7, v26, v30 offset0:130 offset1:162
	ds_write2_b32 v7, v27, v31 offset0:195 offset1:227
	s_waitcnt lgkmcnt(0)
	s_barrier
	ds_read2_b32 v[32:33], v8 offset1:1
	ds_read2_b32 v[34:35], v8 offset0:2 offset1:3
	ds_read2_b32 v[36:37], v8 offset0:4 offset1:5
	ds_read2_b32 v[38:39], v8 offset0:6 offset1:7
	s_waitcnt lgkmcnt(0)
	v_cvt_pk_bf16_f32 v40, v32, v33
	v_cvt_pk_bf16_f32 v41, v34, v35
	v_cvt_pk_bf16_f32 v42, v36, v37
	v_cvt_pk_bf16_f32 v43, v38, v39
	global_store_dwordx4 v13, v[40:43], s[24:25]
	s_cmpk_lt_u32 s4, 0xd00
	s_cbranch_scc0 .Lwt_out_4
	s_movk_i32 s12, 3
	s_movk_i32 s13, 0xa80
	s_cmpk_lt_u32 s4, 0xa80
	s_cselect_b32 s12, 2, s12
	s_cselect_b32 s13, 0x680, s13
	s_cmpk_lt_u32 s4, 0x680
	s_cselect_b32 s12, 1, s12
	s_cselect_b32 s13, 0x280, s13
	s_cmpk_lt_u32 s4, 0x280
	s_cselect_b32 s12, 0, s12
	s_cselect_b32 s13, 0, s13
	s_sub_i32 s13, s4, s13
	s_add_i32 s5, s12, 1
	s_and_b32 s5, s5, 2
	s_movk_i32 s27, 0x2800
	s_cmp_eq_u32 s5, 0
	s_cselect_b32 s10, s27, 0x4000
	s_movk_i32 s27, 0x500
	s_cselect_b32 s11, s27, 0x800
	s_lshl_b32 s5, s12, 1
	s_add_i32 s5, s5, 14
	s_cmp_eq_u32 s12, 0
	s_cselect_b32 s5, 62, s5
	v_readlane_b32 s6, v253, s5
	s_add_i32 s5, s5, 1
	v_readlane_b32 s7, v253, s5
	s_mov_b64 s[8:9], s[70:71]
	s_cmp_eq_u32 s12, 1
	s_cselect_b64 s[8:9], s[72:73], s[8:9]
	s_cmp_eq_u32 s12, 2
	s_cselect_b64 s[8:9], s[74:75], s[8:9]
	s_cmp_eq_u32 s12, 3
	s_cbranch_scc0 .Lwt_com_4
	v_readlane_b32 s8, v253, 0
	v_readlane_b32 s9, v253, 1
	s_branch .Lwt_com_4

; __device__ __forceinline__ void phase0(const Params& p, unsigned char* smem) {
;     ...
;             float4 v[2];
; #pragma unroll
;             for (int i = 0; i < 2; ++i) {
;                 const int kk = (tid >> 4) + 32 * i, n4 = (tid & 15) * 4;
;                 v[i] = *(const float4*)(W + (size_t)(k0 + kk) * N + n0 + n4);
;             }
;             __syncthreads();
; #pragma unroll
;             for (int i = 0; i < 2; ++i) {
;                 const int kk = (tid >> 4) + 32 * i, n4 = (tid & 15) * 4;
;                 sT[(n4 + 0) * 65 + kk] = v[i].x; sT[(n4 + 1) * 65 + kk] = v[i].y;
;                 sT[(n4 + 2) * 65 + kk] = v[i].z; sT[(n4 + 3) * 65 + kk] = v[i].w;
;             }
;             __syncthreads();
;             {
;                 const int n = tid >> 3, k8 = (tid & 7) * 8;
;                 const float* s = sT + n * 65 + k8;
;                 u32x4 o; o.x = pk_bf16(s[0], s[1]); o.y = pk_bf16(s[2], s[3]); o.z = pk_bf16(s[4], s[5]); o.w = pk_bf16(s[6], s[7]);
;                 int f = n0 + n;
;                 if (f < nperm) { const int fl = f & 255, hh = fl >> 6, d = fl & 63; f = (f & ~255) + 128 * (d >> 5) + 32 * hh + (d & 31); }
;                 *(u32x4*)(Wt + (size_t)f * 1024 + k0 + k8) = o;
.Lwt_com_4:
	s_and_b32 s14, s13, 15
	s_lshl_b32 s14, s14, 6
	s_lshr_b32 s15, s13, 4
	s_lshl_b32 s15, s15, 6
	s_mul_i32 s5, s14, s10
	s_lshl_b32 s27, s15, 2
	s_add_u32 s5, s5, s27
	s_add_u32 s16, s6, s5
	s_addc_u32 s17, s7, 0
	s_lshl_b32 s5, s10, 5
	s_add_u32 s18, s16, s5
	s_addc_u32 s19, s17, 0
	v_mul_lo_u32 v11, v5, s10
	v_add_u32_e32 v11, v11, v6
	global_load_dwordx4 v[24:27], v11, s[16:17]
	global_load_dwordx4 v[28:31], v11, s[18:19]
	s_and_b32 s5, s15, 0xffffff00
	s_lshr_b32 s27, s15, 6
	s_and_b32 s27, s27, 3
	s_lshl_b32 s27, s27, 5
	s_add_i32 s5, s5, s27
	s_cmp_lt_u32 s15, s11
	s_cselect_b32 s5, s5, s15
	s_cselect_b64 s[34:35], -1, 0
	v_cndmask_b32_e64 v13, v10, v9, s[34:35]
	s_lshl_b32 s5, s5, 11
	s_lshl_b32 s27, s14, 1
	s_add_u32 s5, s5, s27
	s_add_u32 s24, s8, s5
	s_addc_u32 s25, s9, 0
	s_add_i32 s4, s4, s92
	s_waitcnt vmcnt(3)
	s_barrier
	ds_write2_b32 v7, v16, v20 offset1:32
	ds_write2_b32 v7, v17, v21 offset0:65 offset1:97
	ds_write2_b32 v7, v18, v22 offset0:130 offset1:162
	ds_write2_b32 v7, v19, v23 offset0:195 offset1:227
	s_waitcnt lgkmcnt(0)
	s_barrier
	ds_read2_b32 v[32:33], v8 offset1:1
	ds_read2_b32 v[34:35], v8 offset0:2 offset1:3
	ds_read2_b32 v[36:37], v8 offset0:4 offset1:5
	ds_read2_b32 v[38:39], v8 offset0:6 offset1:7
	s_waitcnt lgkmcnt(0)
	v_cvt_pk_bf16_f32 v40, v32, v33
	v_cvt_pk_bf16_f32 v41, v34, v35
	v_cvt_pk_bf16_f32 v42, v36, v37
	v_cvt_pk_bf16_f32 v43, v38, v39
	global_store_dwordx4 v12, v[40:43], s[20:21]
	s_sub_i32 s26, s26, 1
	s_cmp_lg_u32 s26, 0
	s_cbranch_scc1 .Lwt_loop
	s_cmpk_lt_u32 s4, 0xd00
	s_cbranch_scc0 .Lwt_out_5
	s_movk_i32 s12, 3
	s_movk_i32 s13, 0xa80
	s_cmpk_lt_u32 s4, 0xa80
	s_cselect_b32 s12, 2, s12
	s_cselect_b32 s13, 0x680, s13
	s_cmpk_lt_u32 s4, 0x680
	s_cselect_b32 s12, 1, s12
	s_cselect_b32 s13, 0x280, s13
	s_cmpk_lt_u32 s4, 0x280
	s_cselect_b32 s12, 0, s12
	s_cselect_b32 s13, 0, s13
	s_sub_i32 s13, s4, s13
	s_add_i32 s5, s12, 1
	s_and_b32 s5, s5, 2
	s_movk_i32 s27, 0x2800
	s_cmp_eq_u32 s5, 0
	s_cselect_b32 s10, s27, 0x4000
	s_movk_i32 s27, 0x500
	s_cselect_b32 s11, s27, 0x800
	s_lshl_b32 s5, s12, 1
	s_add_i32 s5, s5, 14
	s_cmp_eq_u32 s12, 0
	s_cselect_b32 s5, 62, s5
	v_readlane_b32 s6, v253, s5
	s_add_i32 s5, s5, 1
	v_readlane_b32 s7, v253, s5
	s_mov_b64 s[8:9], s[70:71]
	s_cmp_eq_u32 s12, 1
	s_cselect_b64 s[8:9], s[72:73], s[8:9]
	s_cmp_eq_u32 s12, 2
	s_cselect_b64 s[8:9], s[74:75], s[8:9]
	s_cmp_eq_u32 s12, 3
	s_cbranch_scc0 .Lwt_com_5
	v_readlane_b32 s8, v253, 0
	v_readlane_b32 s9, v253, 1
	s_branch .Lwt_com_5

; __device__ __forceinline__ void phase0(const Params& p, unsigned char* smem) {
;     ...
;             float4 v[2];
; #pragma unroll
;             for (int i = 0; i < 2; ++i) {
;                 const int kk = (tid >> 4) + 32 * i, n4 = (tid & 15) * 4;
;                 v[i] = *(const float4*)(W + (size_t)(k0 + kk) * N + n0 + n4);
;             }
;             __syncthreads();
; #pragma unroll
;             for (int i = 0; i < 2; ++i) {
;                 const int kk = (tid >> 4) + 32 * i, n4 = (tid & 15) * 4;
;                 sT[(n4 + 0) * 65 + kk] = v[i].x; sT[(n4 + 1) * 65 + kk] = v[i].y;
;                 sT[(n4 + 2) * 65 + kk] = v[i].z; sT[(n4 + 3) * 65 + kk] = v[i].w;
;             }
;             __syncthreads();
;             {
;                 const int n = tid >> 3, k8 = (tid & 7) * 8;
;                 const float* s = sT + n * 65 + k8;
;                 u32x4 o; o.x = pk_bf16(s[0], s[1]); o.y = pk_bf16(s[2], s[3]); o.z = pk_bf16(s[4], s[5]); o.w = pk_bf16(s[6], s[7]);
;                 int f = n0 + n;
;                 if (f < nperm) { const int fl = f & 255, hh = fl >> 6, d = fl & 63; f = (f & ~255) + 128 * (d >> 5) + 32 * hh + (d & 31); }
;                 *(u32x4*)(Wt + (size_t)f * 1024 + k0 + k8) = o;
.Lwt_com_5:
	s_and_b32 s14, s13, 15
	s_lshl_b32 s14, s14, 6
	s_lshr_b32 s15, s13, 4
	s_lshl_b32 s15, s15, 6
	s_mul_i32 s5, s14, s10
	s_lshl_b32 s27, s15, 2
	s_add_u32 s5, s5, s27
	s_add_u32 s16, s6, s5
	s_addc_u32 s17, s7, 0
	s_lshl_b32 s5, s10, 5
	s_add_u32 s18, s16, s5
	s_addc_u32 s19, s17, 0
	v_mul_lo_u32 v11, v5, s10
	v_add_u32_e32 v11, v11, v6
	global_load_dwordx4 v[16:19], v11, s[16:17]
	global_load_dwordx4 v[20:23], v11, s[18:19]
	s_and_b32 s5, s15, 0xffffff00
	s_lshr_b32 s27, s15, 6
	s_and_b32 s27, s27, 3
	s_lshl_b32 s27, s27, 5
	s_add_i32 s5, s5, s27
	s_cmp_lt_u32 s15, s11
	s_cselect_b32 s5, s5, s15
	s_cselect_b64 s[22:23], -1, 0
	v_cndmask_b32_e64 v12, v10, v9, s[22:23]
	s_lshl_b32 s5, s5, 11
	s_lshl_b32 s27, s14, 1
	s_add_u32 s5, s5, s27
	s_add_u32 s20, s8, s5
	s_addc_u32 s21, s9, 0
	s_add_i32 s4, s4, s92
	s_waitcnt vmcnt(3)
	s_barrier
	ds_write2_b32 v7, v24, v28 offset1:32
	ds_write2_b32 v7, v25, v29 offset0:65 offset1:97
	ds_write2_b32 v7, v26, v30 offset0:130 offset1:162
	ds_write2_b32 v7, v27, v31 offset0:195 offset1:227
	s_waitcnt lgkmcnt(0)
	s_barrier
	ds_read2_b32 v[32:33], v8 offset1:1
	ds_read2_b32 v[34:35], v8 offset0:2 offset1:3
	ds_read2_b32 v[36:37], v8 offset0:4 offset1:5
	ds_read2_b32 v[38:39], v8 offset0:6 offset1:7
	s_waitcnt lgkmcnt(0)
	v_cvt_pk_bf16_f32 v40, v32, v33
	v_cvt_pk_bf16_f32 v41, v34, v35
	v_cvt_pk_bf16_f32 v42, v36, v37
	v_cvt_pk_bf16_f32 v43, v38, v39
	global_store_dwordx4 v13, v[40:43], s[24:25]
	s_waitcnt vmcnt(1)
	s_barrier
	ds_write2_b32 v7, v16, v20 offset1:32
	ds_write2_b32 v7, v17, v21 offset0:65 offset1:97
	ds_write2_b32 v7, v18, v22 offset0:130 offset1:162
	ds_write2_b32 v7, v19, v23 offset0:195 offset1:227
	s_waitcnt lgkmcnt(0)
	s_barrier
	ds_read2_b32 v[32:33], v8 offset1:1
	ds_read2_b32 v[34:35], v8 offset0:2 offset1:3
	ds_read2_b32 v[36:37], v8 offset0:4 offset1:5
	ds_read2_b32 v[38:39], v8 offset0:6 offset1:7
	s_waitcnt lgkmcnt(0)
	v_cvt_pk_bf16_f32 v40, v32, v33
	v_cvt_pk_bf16_f32 v41, v34, v35
	v_cvt_pk_bf16_f32 v42, v36, v37
	v_cvt_pk_bf16_f32 v43, v38, v39
	global_store_dwordx4 v12, v[40:43], s[20:21]
	s_load_dwordx16 s[4:19], s[0:1], 0x0
